# attention key loop: one static s_setprio 1 for waves 4-7, reset after the loop
# speedup vs baseline: 1.0041x; 1.0041x over previous
.Lattn_p1:
	s_waitcnt lgkmcnt(0)
	s_barrier
	v_readfirstlane_b32 s8, v181
	s_nop 3
	s_cmp_ge_u32 s8, 0x100
	s_cbranch_scc0 .Lattn_noprio
	s_setprio 1
.Lattn_noprio:
	s_branch .LBB0_1262
.LBB0_1260:
	v_sub_f32_e32 v0, v96, v209
	v_exp_f32_e32 v0, v0
	v_sub_f32_e32 v2, v97, v209
	v_exp_f32_e32 v6, v2
	v_sub_f32_e32 v2, v98, v209
	v_exp_f32_e32 v7, v2
	v_add_f32_e32 v2, 0, v0
	v_add_f32_e32 v2, v6, v2
	v_sub_f32_e32 v8, v103, v209
	v_add_f32_e32 v14, v7, v2
	v_sub_f32_e32 v2, v99, v209
	v_exp_f32_e32 v15, v2
	v_sub_f32_e32 v2, v100, v209
	v_exp_f32_e32 v96, v2
	v_sub_f32_e32 v2, v101, v209
	v_exp_f32_e32 v97, v2
	v_sub_f32_e32 v2, v102, v209
	v_add_u32_e32 v99, 0x6000, v242
	v_exp_f32_e32 v98, v2
	ds_read_b128 v[2:5], v247
	v_exp_f32_e32 v100, v8
	v_cvt_pk_bf16_f32 v6, v0, v6
	v_add_u32_e32 v0, 0x7000, v242
	ds_read_b128 v[10:13], v247 offset:4608
	v_cvt_pk_bf16_f32 v7, v7, v15
	v_cvt_pk_bf16_f32 v8, v96, v97
	v_cvt_pk_bf16_f32 v9, v98, v100
	v_add_u32_e32 v101, 0x8000, v242
	s_waitcnt lgkmcnt(1)
	v_mfma_f32_32x32x16_bf16 v[64:79], v[2:5], v[6:9], v[64:79]
	v_add_f32_e32 v2, v15, v14
	v_add_f32_e32 v14, v96, v2
	v_sub_f32_e32 v2, v104, v209
	v_exp_f32_e32 v15, v2
	ds_read_b128 v[2:5], v247 offset:9216
	v_add_u32_e32 v104, 0x9000, v242
	v_sub_f32_e32 v96, v105, v209
	s_waitcnt lgkmcnt(1)
	v_mfma_f32_32x32x16_bf16 v[48:63], v[10:13], v[6:9], v[48:63]
	v_sub_f32_e32 v10, v106, v209
	v_exp_f32_e32 v102, v10
	v_sub_f32_e32 v10, v107, v209
	v_exp_f32_e32 v103, v10
	ds_read_b128 v[10:13], v247 offset:13824
	v_exp_f32_e32 v96, v96
	s_waitcnt lgkmcnt(1)
	v_mfma_f32_32x32x16_bf16 v[32:47], v[2:5], v[6:9], v[32:47]
	v_sub_f32_e32 v2, v108, v209
	v_exp_f32_e32 v105, v2
	v_sub_f32_e32 v2, v109, v209
	v_exp_f32_e32 v106, v2
	v_sub_f32_e32 v2, v110, v209
	v_exp_f32_e32 v107, v2
	ds_read_b128 v[2:5], v247 offset:32
	s_waitcnt lgkmcnt(1)
	v_mfma_f32_32x32x16_bf16 v[16:31], v[10:13], v[6:9], v[16:31]
	v_sub_f32_e32 v6, v111, v209
	v_exp_f32_e32 v108, v6
	ds_read_b128 v[10:13], v247 offset:4640
	v_cvt_pk_bf16_f32 v6, v15, v96
	v_cvt_pk_bf16_f32 v7, v102, v103
	v_cvt_pk_bf16_f32 v8, v105, v106
	v_cvt_pk_bf16_f32 v9, v107, v108
	s_waitcnt lgkmcnt(1)
	s_nop 0
	v_mfma_f32_32x32x16_bf16 v[64:79], v[2:5], v[6:9], v[64:79]
	v_add_f32_e32 v2, v97, v14
	v_add_f32_e32 v2, v98, v2
	v_add_f32_e32 v2, v100, v2
	v_add_f32_e32 v14, v15, v2
	v_sub_f32_e32 v2, v80, v209
	v_exp_f32_e32 v15, v2
	ds_read_b128 v[2:5], v247 offset:9248
	s_waitcnt lgkmcnt(1)
	v_mfma_f32_32x32x16_bf16 v[48:63], v[10:13], v[6:9], v[48:63]
	v_sub_f32_e32 v10, v81, v209
	v_exp_f32_e32 v80, v10
	v_sub_f32_e32 v10, v82, v209
	v_exp_f32_e32 v81, v10
	v_sub_f32_e32 v10, v83, v209
	v_exp_f32_e32 v82, v10
	ds_read_b128 v[10:13], v247 offset:13856
	s_waitcnt lgkmcnt(1)
	v_mfma_f32_32x32x16_bf16 v[32:47], v[2:5], v[6:9], v[32:47]
	v_sub_f32_e32 v2, v84, v209
	v_exp_f32_e32 v83, v2
	v_sub_f32_e32 v2, v85, v209
	v_exp_f32_e32 v84, v2
	v_sub_f32_e32 v2, v86, v209
	v_exp_f32_e32 v85, v2
	ds_read_b128 v[2:5], v247 offset:64
	s_waitcnt lgkmcnt(1)
	v_mfma_f32_32x32x16_bf16 v[16:31], v[10:13], v[6:9], v[16:31]
	v_sub_f32_e32 v6, v87, v209
	v_exp_f32_e32 v86, v6
	ds_read_b128 v[10:13], v247 offset:4672
	v_cvt_pk_bf16_f32 v6, v15, v80
	v_cvt_pk_bf16_f32 v7, v81, v82
	v_cvt_pk_bf16_f32 v8, v83, v84
	v_cvt_pk_bf16_f32 v9, v85, v86
	s_waitcnt lgkmcnt(1)
	s_nop 0
	v_mfma_f32_32x32x16_bf16 v[64:79], v[2:5], v[6:9], v[64:79]
	v_add_f32_e32 v2, v96, v14
	v_add_f32_e32 v2, v102, v2
	v_add_f32_e32 v2, v103, v2
	v_add_f32_e32 v14, v105, v2
	v_sub_f32_e32 v2, v88, v209
	v_exp_f32_e32 v87, v2
	ds_read_b128 v[2:5], v247 offset:9280
	s_waitcnt lgkmcnt(1)
	v_mfma_f32_32x32x16_bf16 v[48:63], v[10:13], v[6:9], v[48:63]
	v_sub_f32_e32 v10, v89, v209
	v_exp_f32_e32 v88, v10
	v_sub_f32_e32 v10, v90, v209
	v_exp_f32_e32 v89, v10
	v_sub_f32_e32 v10, v91, v209
	v_exp_f32_e32 v90, v10
	ds_read_b128 v[10:13], v247 offset:13888
	s_waitcnt lgkmcnt(1)
	v_mfma_f32_32x32x16_bf16 v[32:47], v[2:5], v[6:9], v[32:47]
	v_sub_f32_e32 v2, v92, v209
	v_exp_f32_e32 v91, v2
	v_sub_f32_e32 v2, v93, v209
	v_exp_f32_e32 v92, v2
	v_sub_f32_e32 v2, v94, v209
	v_exp_f32_e32 v93, v2
	ds_read_b128 v[2:5], v247 offset:96
	s_waitcnt lgkmcnt(1)
	v_mfma_f32_32x32x16_bf16 v[16:31], v[10:13], v[6:9], v[16:31]
	ds_read_b128 v[10:13], v247 offset:4704
	v_sub_f32_e32 v6, v95, v209
	v_exp_f32_e32 v94, v6
	v_add_f32_e32 v0, v106, v14
	v_add_f32_e32 v0, v107, v0
	v_cvt_pk_bf16_f32 v6, v87, v88
	v_cvt_pk_bf16_f32 v7, v89, v90
	v_cvt_pk_bf16_f32 v8, v91, v92
	v_cvt_pk_bf16_f32 v9, v93, v94
	v_add_f32_e32 v0, v108, v0
	v_add_f32_e32 v0, v15, v0
	s_waitcnt lgkmcnt(1)
	v_mfma_f32_32x32x16_bf16 v[64:79], v[2:5], v[6:9], v[64:79]
	ds_read_b128 v[2:5], v247 offset:9312
	v_add_f32_e32 v0, v80, v0
	v_add_f32_e32 v0, v81, v0
	v_add_f32_e32 v0, v82, v0
	v_add_f32_e32 v0, v83, v0
	v_add_f32_e32 v0, v84, v0
	v_add_f32_e32 v0, v85, v0
	s_waitcnt lgkmcnt(1)
	v_mfma_f32_32x32x16_bf16 v[48:63], v[10:13], v[6:9], v[48:63]
	ds_read_b128 v[10:13], v247 offset:13920
	v_add_f32_e32 v0, v86, v0
	v_add_f32_e32 v0, v87, v0
	v_add_f32_e32 v0, v88, v0
	v_add_f32_e32 v0, v89, v0
	v_add_f32_e32 v0, v90, v0
	v_add_f32_e32 v0, v91, v0
	s_waitcnt lgkmcnt(1)
	v_mfma_f32_32x32x16_bf16 v[32:47], v[2:5], v[6:9], v[32:47]
	v_add_f32_e32 v0, v92, v0
	v_add_f32_e32 v0, v93, v0
	v_add_f32_e32 v0, v94, v0
	v_add_f32_e32 v205, v205, v0
	s_waitcnt lgkmcnt(0)
	v_mfma_f32_32x32x16_bf16 v[16:31], v[10:13], v[6:9], v[16:31]

.LBB0_1270:
	s_setprio 0
	ds_bpermute_b32 v0, v218, v205
	s_waitcnt vmcnt(0)
	ds_read2st64_b64 v[2:5], v219 offset1:16
	ds_read2st64_b64 v[6:9], v220 offset1:16
	v_ashrrev_i32_e32 v207, 31, v206
	s_lshl_b32 s8, s41, 24
	s_waitcnt lgkmcnt(0)
	v_add_f32_e32 v0, v205, v0
	v_div_scale_f32 v10, s[0:1], v0, v0, 1.0
	v_rcp_f32_e32 v11, v10
	v_div_scale_f32 v12, vcc, 1.0, v0, 1.0
	s_mov_b64 s[10:11], 0
	v_fma_f32 v13, -v10, v11, 1.0
	v_fmac_f32_e32 v11, v13, v11
	v_mul_f32_e32 v13, v12, v11
	v_fma_f32 v14, -v10, v13, v12
	v_fmac_f32_e32 v13, v14, v11
	v_fma_f32 v10, -v10, v13, v12
	v_div_fmas_f32 v10, v10, v11, v13
	v_div_fixup_f32 v0, v10, v0, 1.0
	v_pk_mul_f32 v[10:11], v[64:65], v[0:1] op_sel_hi:[1,0]
	v_pk_mul_f32 v[12:13], v[66:67], v[0:1] op_sel_hi:[1,0]
	v_mov_b32_e32 v64, v2
	v_mov_b32_e32 v65, v3
	v_mov_b32_e32 v66, v6
	v_mov_b32_e32 v67, v7
	v_pk_mul_f32 v[2:3], v[68:69], v[0:1] op_sel_hi:[1,0]
	v_cvt_pk_bf16_f32 v10, v10, v11
	v_cvt_pk_bf16_f32 v11, v12, v13
	v_cvt_pk_bf16_f32 v12, v2, v3
	v_pk_mul_f32 v[2:3], v[70:71], v[0:1] op_sel_hi:[1,0]
	v_mov_b32_e32 v6, v4
	v_cvt_pk_bf16_f32 v13, v2, v3
	v_mov_b32_e32 v7, v5
	s_nop 0
	v_mfma_f32_32x32x16_bf16 v[128:143], v[64:67], v[10:13], 0
	ds_read2st64_b64 v[2:5], v219 offset0:32 offset1:48
	ds_read2st64_b64 v[64:67], v220 offset0:32 offset1:48
	v_mfma_f32_32x32x16_bf16 v[112:127], v[6:9], v[10:13], 0
	s_waitcnt lgkmcnt(1)
	v_mov_b32_e32 v6, v2
	v_mov_b32_e32 v7, v3
	s_waitcnt lgkmcnt(0)
	v_mov_b32_e32 v8, v64
	v_mov_b32_e32 v9, v65
	v_mov_b32_e32 v64, v4
	v_mov_b32_e32 v65, v5
	ds_read2st64_b64 v[2:5], v221 offset1:16
	v_mfma_f32_32x32x16_bf16 v[96:111], v[6:9], v[10:13], 0
	v_mul_f32_e64 v6, v72, v0
	v_mul_f32_e64 v7, v73, v0
	v_mul_f32_e64 v8, v74, v0
	v_mul_f32_e64 v9, v75, v0
	v_cvt_pk_bf16_f32 v6, v6, v7
	v_cvt_pk_bf16_f32 v7, v8, v9
	v_mfma_f32_32x32x16_bf16 v[80:95], v[64:67], v[10:13], 0
	ds_read2st64_b64 v[10:13], v222 offset1:16
	s_waitcnt lgkmcnt(1)
	v_mov_b32_e32 v64, v2
	v_mov_b32_e32 v65, v3
	v_mul_f32_e64 v2, v76, v0
	v_mul_f32_e64 v3, v77, v0
	s_waitcnt lgkmcnt(0)
	v_mov_b32_e32 v66, v10
	v_mov_b32_e32 v67, v11
	v_cvt_pk_bf16_f32 v8, v2, v3
	v_pk_mul_f32 v[2:3], v[78:79], v[0:1] op_sel_hi:[1,0]
	v_mov_b32_e32 v10, v4
	v_cvt_pk_bf16_f32 v9, v2, v3
	v_mov_b32_e32 v11, v5
	s_nop 0
	v_mfma_f32_32x32x16_bf16 v[128:143], v[64:67], v[6:9], v[128:143]
	ds_read2st64_b64 v[2:5], v221 offset0:32 offset1:48
	ds_read2st64_b64 v[64:67], v222 offset0:32 offset1:48
	v_mfma_f32_32x32x16_bf16 v[112:127], v[10:13], v[6:9], v[112:127]
	s_waitcnt lgkmcnt(1)
	v_mov_b32_e32 v10, v2
	v_mov_b32_e32 v11, v3
	s_waitcnt lgkmcnt(0)
	v_mov_b32_e32 v12, v64
	v_mov_b32_e32 v13, v65
	v_mov_b32_e32 v64, v4
	v_mov_b32_e32 v65, v5
	ds_read2st64_b64 v[2:5], v223 offset1:16
	v_mfma_f32_32x32x16_bf16 v[96:111], v[10:13], v[6:9], v[96:111]
	ds_read2st64_b64 v[10:13], v224 offset1:16
	v_mfma_f32_32x32x16_bf16 v[80:95], v[64:67], v[6:9], v[80:95]
	v_mul_f32_e64 v6, v48, v0
	v_mul_f32_e64 v7, v49, v0
	v_mul_f32_e64 v8, v50, v0
	v_mul_f32_e64 v9, v51, v0
	s_waitcnt lgkmcnt(1)
	v_mov_b32_e32 v48, v2
	v_mov_b32_e32 v49, v3
	s_waitcnt lgkmcnt(0)
	v_mov_b32_e32 v50, v10
	v_mov_b32_e32 v51, v11
	v_pk_mul_f32 v[2:3], v[52:53], v[0:1] op_sel_hi:[1,0]
	v_cvt_pk_bf16_f32 v6, v6, v7
	v_cvt_pk_bf16_f32 v7, v8, v9
	v_cvt_pk_bf16_f32 v8, v2, v3
	v_pk_mul_f32 v[2:3], v[54:55], v[0:1] op_sel_hi:[1,0]
	v_mov_b32_e32 v10, v4
	v_cvt_pk_bf16_f32 v9, v2, v3
	v_mov_b32_e32 v11, v5
	s_nop 0
	v_mfma_f32_32x32x16_bf16 v[128:143], v[48:51], v[6:9], v[128:143]
	ds_read2st64_b64 v[2:5], v223 offset0:32 offset1:48
	ds_read2st64_b64 v[48:51], v224 offset0:32 offset1:48
	v_mfma_f32_32x32x16_bf16 v[112:127], v[10:13], v[6:9], v[112:127]
	s_waitcnt lgkmcnt(1)
	v_mov_b32_e32 v10, v2
	v_mov_b32_e32 v11, v3
	s_waitcnt lgkmcnt(0)
	v_mov_b32_e32 v12, v48
	v_mov_b32_e32 v13, v49
	v_mov_b32_e32 v48, v4
	v_mov_b32_e32 v49, v5
	ds_read2st64_b64 v[2:5], v225 offset1:16
	v_mfma_f32_32x32x16_bf16 v[96:111], v[10:13], v[6:9], v[96:111]
	ds_read2st64_b64 v[10:13], v226 offset1:16
	v_mfma_f32_32x32x16_bf16 v[80:95], v[48:51], v[6:9], v[80:95]
	s_waitcnt lgkmcnt(1)
	v_mov_b32_e32 v48, v2
	v_mov_b32_e32 v49, v3
	s_waitcnt lgkmcnt(0)
	v_mov_b32_e32 v50, v10
	v_mov_b32_e32 v51, v11
	v_pk_mul_f32 v[6:7], v[56:57], v[0:1] op_sel_hi:[1,0]
	v_pk_mul_f32 v[8:9], v[58:59], v[0:1] op_sel_hi:[1,0]
	v_pk_mul_f32 v[2:3], v[60:61], v[0:1] op_sel_hi:[1,0]
	v_cvt_pk_bf16_f32 v6, v6, v7
	v_cvt_pk_bf16_f32 v7, v8, v9
	v_cvt_pk_bf16_f32 v8, v2, v3
	v_pk_mul_f32 v[2:3], v[62:63], v[0:1] op_sel_hi:[1,0]
	v_mov_b32_e32 v10, v4
	v_cvt_pk_bf16_f32 v9, v2, v3
	v_mov_b32_e32 v11, v5
	s_nop 0
	v_mfma_f32_32x32x16_bf16 v[128:143], v[48:51], v[6:9], v[128:143]
	ds_read2st64_b64 v[2:5], v225 offset0:32 offset1:48
	ds_read2st64_b64 v[48:51], v226 offset0:32 offset1:48
	v_mfma_f32_32x32x16_bf16 v[112:127], v[10:13], v[6:9], v[112:127]
	s_waitcnt lgkmcnt(1)
	v_mov_b32_e32 v10, v2
	v_mov_b32_e32 v11, v3
	s_waitcnt lgkmcnt(0)
	v_mov_b32_e32 v12, v48
	v_mov_b32_e32 v13, v49
	v_mov_b32_e32 v48, v4
	v_mov_b32_e32 v49, v5
	ds_read2st64_b64 v[2:5], v227 offset1:16
	v_mfma_f32_32x32x16_bf16 v[96:111], v[10:13], v[6:9], v[96:111]
	ds_read2st64_b64 v[10:13], v228 offset1:16
	v_mfma_f32_32x32x16_bf16 v[80:95], v[48:51], v[6:9], v[80:95]
	v_mul_f32_e64 v6, v32, v0
	v_mul_f32_e64 v7, v33, v0
	v_mul_f32_e64 v8, v34, v0
	v_mul_f32_e64 v9, v35, v0
	s_waitcnt lgkmcnt(1)
	v_mov_b32_e32 v32, v2
	v_mov_b32_e32 v33, v3
	s_waitcnt lgkmcnt(0)
	v_mov_b32_e32 v34, v10
	v_mov_b32_e32 v35, v11
	v_pk_mul_f32 v[2:3], v[36:37], v[0:1] op_sel_hi:[1,0]
	v_cvt_pk_bf16_f32 v6, v6, v7
	v_cvt_pk_bf16_f32 v7, v8, v9
	v_cvt_pk_bf16_f32 v8, v2, v3
	v_pk_mul_f32 v[2:3], v[38:39], v[0:1] op_sel_hi:[1,0]
	v_mov_b32_e32 v10, v4
	v_cvt_pk_bf16_f32 v9, v2, v3
	v_mov_b32_e32 v11, v5
	s_nop 0
	v_mfma_f32_32x32x16_bf16 v[128:143], v[32:35], v[6:9], v[128:143]
	ds_read2st64_b64 v[2:5], v227 offset0:32 offset1:48
	ds_read2st64_b64 v[32:35], v228 offset0:32 offset1:48
	v_mfma_f32_32x32x16_bf16 v[112:127], v[10:13], v[6:9], v[112:127]
	s_waitcnt lgkmcnt(1)
	v_mov_b32_e32 v10, v2
	v_mov_b32_e32 v11, v3
	s_waitcnt lgkmcnt(0)
	v_mov_b32_e32 v12, v32
	v_mov_b32_e32 v13, v33
	v_mov_b32_e32 v32, v4
	v_mov_b32_e32 v33, v5
	v_pk_mul_f32 v[2:3], v[40:41], v[0:1] op_sel_hi:[1,0]
	v_mfma_f32_32x32x16_bf16 v[96:111], v[10:13], v[6:9], v[96:111]
	ds_read2st64_b64 v[10:13], v229 offset1:16
	v_mul_f32_e64 v4, v42, v0
	v_mul_f32_e64 v5, v43, v0
	v_cvt_pk_bf16_f32 v2, v2, v3
	v_cvt_pk_bf16_f32 v3, v4, v5
	v_pk_mul_f32 v[4:5], v[44:45], v[0:1] op_sel_hi:[1,0]
	s_nop 0
	v_cvt_pk_bf16_f32 v4, v4, v5
	v_mfma_f32_32x32x16_bf16 v[80:95], v[32:35], v[6:9], v[80:95]
	ds_read2st64_b64 v[6:9], v230 offset1:16
	s_waitcnt lgkmcnt(1)
	v_mov_b32_e32 v32, v10
	v_mov_b32_e32 v33, v11
	s_waitcnt lgkmcnt(0)
	v_mov_b32_e32 v34, v6
	v_mov_b32_e32 v35, v7
	v_pk_mul_f32 v[6:7], v[46:47], v[0:1] op_sel_hi:[1,0]
	s_nop 0
	v_cvt_pk_bf16_f32 v5, v6, v7
	v_mov_b32_e32 v6, v12
	v_mov_b32_e32 v7, v13
	v_mfma_f32_32x32x16_bf16 v[128:143], v[32:35], v[2:5], v[128:143]
	ds_read2st64_b64 v[10:13], v229 offset0:32 offset1:48
	ds_read2st64_b64 v[32:35], v230 offset0:32 offset1:48
	v_mfma_f32_32x32x16_bf16 v[112:127], v[6:9], v[2:5], v[112:127]
	s_waitcnt lgkmcnt(1)
	v_mov_b32_e32 v6, v10
	v_mov_b32_e32 v7, v11
	s_waitcnt lgkmcnt(0)
	v_mov_b32_e32 v8, v32
	v_mov_b32_e32 v9, v33
	v_mov_b32_e32 v32, v12
	v_mov_b32_e32 v33, v13
	v_pk_mul_f32 v[10:11], v[16:17], v[0:1] op_sel_hi:[1,0]
	v_mfma_f32_32x32x16_bf16 v[96:111], v[6:9], v[2:5], v[96:111]
	v_mul_f32_e64 v12, v18, v0
	v_mul_f32_e64 v13, v19, v0
	v_cvt_pk_bf16_f32 v10, v10, v11
	v_cvt_pk_bf16_f32 v11, v12, v13
	ds_read2st64_b64 v[6:9], v231 offset1:16
	ds_read2st64_b64 v[14:17], v232 offset1:16
	s_waitcnt lgkmcnt(1)
	v_mov_b32_e32 v36, v6
	v_mfma_f32_32x32x16_bf16 v[80:95], v[32:35], v[2:5], v[80:95]
	v_mul_f32_e64 v2, v20, v0
	v_mul_f32_e64 v3, v21, v0
	ds_read2st64_b64 v[18:21], v232 offset0:32 offset1:48
	v_cvt_pk_bf16_f32 v12, v2, v3
	v_mul_f32_e64 v2, v22, v0
	v_mul_f32_e64 v3, v23, v0
	v_mov_b32_e32 v37, v7
	v_cvt_pk_bf16_f32 v13, v2, v3
	ds_read2st64_b64 v[2:5], v231 offset0:32 offset1:48
	s_waitcnt lgkmcnt(2)
	v_mov_b32_e32 v38, v14
	v_mov_b32_e32 v39, v15
	v_mov_b32_e32 v14, v8
	v_mov_b32_e32 v15, v9
	s_waitcnt lgkmcnt(0)
	v_mov_b32_e32 v6, v2
	v_mov_b32_e32 v7, v3
	v_mov_b32_e32 v8, v18
	v_mov_b32_e32 v9, v19
	v_mov_b32_e32 v18, v4
	v_mov_b32_e32 v19, v5
	v_mfma_f32_32x32x16_bf16 v[112:127], v[14:17], v[10:13], v[112:127]
	ds_read2st64_b64 v[14:17], v234 offset1:16
	v_mul_f32_e64 v2, v24, v0
	v_mul_f32_e64 v3, v25, v0
	v_mul_f32_e64 v4, v26, v0
	v_mul_f32_e64 v5, v27, v0
	v_cvt_pk_bf16_f32 v2, v2, v3
	v_cvt_pk_bf16_f32 v3, v4, v5
	v_pk_mul_f32 v[4:5], v[28:29], v[0:1] op_sel_hi:[1,0]
	v_pk_mul_f32 v[22:23], v[30:31], v[0:1] op_sel_hi:[1,0]
	v_mfma_f32_32x32x16_bf16 v[96:111], v[6:9], v[10:13], v[96:111]
	ds_read2st64_b64 v[6:9], v233 offset1:16
	v_cvt_pk_bf16_f32 v4, v4, v5
	v_cvt_pk_bf16_f32 v5, v22, v23
	s_waitcnt lgkmcnt(1)
	v_mov_b32_e32 v24, v14
	v_mov_b32_e32 v25, v15
	s_waitcnt lgkmcnt(0)
	v_mov_b32_e32 v22, v6
	v_mov_b32_e32 v23, v7
	v_mfma_f32_32x32x16_bf16 v[128:143], v[36:39], v[10:13], v[128:143]
	v_mov_b32_e32 v14, v8
	v_mov_b32_e32 v15, v9
	v_mov_b32_e32 v0, v235
	v_mfma_f32_32x32x16_bf16 v[80:95], v[18:21], v[10:13], v[80:95]
	ds_read2st64_b64 v[10:13], v233 offset0:32 offset1:48
	ds_read2st64_b64 v[18:21], v234 offset0:32 offset1:48
	s_waitcnt lgkmcnt(0)
	s_barrier
	v_mov_b32_e32 v6, v10
	v_mov_b32_e32 v7, v11
	v_mov_b32_e32 v8, v18
	v_mov_b32_e32 v9, v19
	v_mfma_f32_32x32x16_bf16 v[128:143], v[22:25], v[2:5], v[128:143]
	v_mov_b32_e32 v18, v12
	v_mov_b32_e32 v19, v13
	v_mfma_f32_32x32x16_bf16 v[112:127], v[14:17], v[2:5], v[112:127]
	s_nop 8
	v_cvt_pk_bf16_f32 v10, v128, v129
	v_cvt_pk_bf16_f32 v11, v130, v131
	v_cvt_pk_bf16_f32 v12, v132, v133
	v_cvt_pk_bf16_f32 v13, v134, v135
	ds_write2_b64 v243, v[10:11], v[12:13] offset1:2
	v_mfma_f32_32x32x16_bf16 v[96:111], v[6:9], v[2:5], v[96:111]
	v_cvt_pk_bf16_f32 v6, v136, v137
	v_cvt_pk_bf16_f32 v7, v138, v139
	v_cvt_pk_bf16_f32 v8, v140, v141
	v_cvt_pk_bf16_f32 v9, v142, v143
	ds_write2_b64 v243, v[6:7], v[8:9] offset0:4 offset1:6
	v_cvt_pk_bf16_f32 v6, v112, v113
	v_cvt_pk_bf16_f32 v7, v114, v115
	v_mfma_f32_32x32x16_bf16 v[80:95], v[18:21], v[2:5], v[80:95]
	v_cvt_pk_bf16_f32 v2, v116, v117
	v_cvt_pk_bf16_f32 v3, v118, v119
	ds_write2_b64 v243, v[6:7], v[2:3] offset0:8 offset1:10
	v_cvt_pk_bf16_f32 v2, v120, v121
	v_cvt_pk_bf16_f32 v3, v122, v123
	v_cvt_pk_bf16_f32 v4, v124, v125
	v_cvt_pk_bf16_f32 v5, v126, v127
	ds_write2_b64 v243, v[2:3], v[4:5] offset0:12 offset1:14
	v_cvt_pk_bf16_f32 v2, v96, v97
	v_cvt_pk_bf16_f32 v3, v98, v99
	v_cvt_pk_bf16_f32 v4, v100, v101
	v_cvt_pk_bf16_f32 v5, v102, v103
	ds_write2_b64 v243, v[2:3], v[4:5] offset0:16 offset1:18
	v_cvt_pk_bf16_f32 v2, v104, v105
	v_cvt_pk_bf16_f32 v3, v106, v107
	v_cvt_pk_bf16_f32 v4, v108, v109
	v_cvt_pk_bf16_f32 v5, v110, v111
	ds_write2_b64 v243, v[2:3], v[4:5] offset0:20 offset1:22
	v_cvt_pk_bf16_f32 v2, v80, v81
	v_cvt_pk_bf16_f32 v3, v82, v83
	v_cvt_pk_bf16_f32 v4, v84, v85
	v_cvt_pk_bf16_f32 v5, v86, v87
	ds_write2_b64 v243, v[2:3], v[4:5] offset0:24 offset1:26
	v_cvt_pk_bf16_f32 v2, v88, v89
	v_cvt_pk_bf16_f32 v3, v90, v91
	v_cvt_pk_bf16_f32 v4, v92, v93
	v_cvt_pk_bf16_f32 v5, v94, v95
	ds_write2_b64 v243, v[2:3], v[4:5] offset0:28 offset1:30
	v_lshlrev_b64 v[2:3], 12, v[206:207]
	s_waitcnt lgkmcnt(0)
	v_lshl_add_u64 v[2:3], s[8:9], 0, v[2:3]
	v_lshl_or_b32 v2, s40, 8, v2
	v_lshl_add_u64 v[2:3], v[202:203], 0, v[2:3]
